# attention work queue per XCC: XCC x processes the units of (batch, kv-head) combination x so that combination's K/V stay in its L2 (global queue kept as fallback)
# baseline (speedup 1.0000x reference)
.LBB0_144:
	s_barrier
	s_and_saveexec_b64 s[0:1], s[34:35]
	s_cbranch_execz .LBB0_148
	s_mov_b64 s[4:5], exec
	v_mbcnt_lo_u32_b32 v0, s4, 0
	v_mbcnt_hi_u32_b32 v0, s5, v0
	v_cmp_eq_u32_e32 vcc, 0, v0
	s_and_saveexec_b64 s[2:3], vcc
	s_cbranch_execz .LBB0_147
	s_bcnt1_i32_b64 s4, s[4:5]
	v_mov_b32_e32 v2, s4
	v_readlane_b32 s4, v236, 60
	v_readlane_b32 s5, v236, 61
	v_readlane_b32 s6, v234, 25
	s_mov_b32 s7, -1
	s_cmp_eq_u32 s6, 1
	s_cbranch_scc0 .Luq_glob
	s_getreg_b32 s7, hwreg(HW_REG_XCC_ID, 0, 4)
	s_lshl_b32 s6, s7, 2
	v_mov_b32_e32 v3, s6
	s_nop 1
	global_atomic_add v2, v3, v2, s[4:5] sc0
	s_branch .Luq_done
.Luq_glob:
	s_nop 1
	global_atomic_add v2, v1, v2, s[4:5] sc0
.Luq_done:
.LBB0_147:
	s_or_b64 exec, exec, s[2:3]
	s_mov_b64 s[2:3], src_shared_base
	s_waitcnt vmcnt(0)
	v_readfirstlane_b32 s2, v2
	s_cmp_eq_u32 s7, -1
	s_cbranch_scc1 .Luq_keep
	s_lshl_b32 s2, s2, 3
	s_or_b32 s2, s2, s7
.Luq_keep:
	v_mov_b32_e32 v177, s3
	s_nop 0
	v_add_u32_e32 v0, s2, v0
	flat_store_dword v[176:177], v0 sc0 sc1
	s_waitcnt vmcnt(0)
